# phase 4: blocks 256..287 (assumed CU partners of the 32 scan blocks) take no work-list items, others renumbered
# speedup vs baseline: 1.0075x; 1.0055x over previous
; DI void phase_scan(const Params& p, char* smem) {
;     ...
;   if (gridDim.x >= 64) {
;     if (blockIdx.x < 32) {
;       __builtin_amdgcn_s_setprio(3);
;       scan_item(p, blockIdx.x, smem);
;       __builtin_amdgcn_s_setprio(0);
;     } else {
;       const int nb = gridDim.x - 32, bi = blockIdx.x - 32;
;       for (int w = bi; w < 640 + 512 + 2112; w += nb) {
;         if (w < 640) branch_a_unit(p, w, smem);
;         else if (w < 1152) delta_sample_item(p, w - 640, smem);
;         else transpose_item(p, transpose_late(w - 1152), (float*)smem);
;       }
.LBB0_607:
	s_and_b64 vcc, exec, s[0:1]
	s_cbranch_vccz .LBB0_704
	s_cmp_gt_u32 s46, 31
	s_mov_b64 s[0:1], -1
	s_cbranch_scc0 .LBB0_698
	s_sub_i32 s33, s46, 32
	s_cmpk_gt_i32 s33, 0xcbf
	s_cbranch_scc1 .LBB0_697
	s_mov_b32 s100, s46
	s_mov_b32 s101, s34
	s_cmp_lt_u32 s46, 0x100
	s_cbranch_scc1 .Liso_ok
	s_cmp_lt_u32 s46, 0x120
	s_cbranch_scc1 .LBB0_697
	s_sub_u32 s46, s46, 32
.Liso_ok:
	s_sub_u32 s34, s34, 32
	s_sub_i32 s33, s46, 32
	v_add_u32_e32 v4, 0x900, v196
	v_lshrrev_b32_e32 v142, 6, v4
	v_add_u32_e32 v4, 0xa00, v196
	v_lshrrev_b32_e32 v143, 6, v4
	v_add_u32_e32 v4, 0xb00, v196
	v_lshrrev_b32_e32 v144, 6, v4
	v_add_u32_e32 v4, 0xd00, v196
	v_lshrrev_b32_e32 v146, 6, v4
	v_add_u32_e32 v4, 0xe00, v196
	v_add_u32_e32 v3, 0x200, v196
	v_lshrrev_b32_e32 v147, 6, v4
	v_add_u32_e32 v4, 0xf00, v196
	v_add_u32_e32 v6, 0x300, v196
	v_lshrrev_b32_e32 v148, 6, v4
	v_lshlrev_b32_e32 v4, 1, v196
	v_lshrrev_b32_e32 v68, 5, v3
	s_movk_i32 s0, 0x104
	v_lshrrev_b32_e32 v69, 6, v3
	v_or_b32_e32 v8, 0x400, v196
	v_and_b32_e32 v149, 62, v4
	v_lshlrev_b32_e32 v3, 2, v68
	v_lshrrev_b32_e32 v70, 5, v6
	v_add_u32_e32 v9, 0x500, v196
	v_mad_u32_u24 v152, v149, s0, v3
	v_lshlrev_b32_e32 v3, 2, v70
	v_lshrrev_b32_e32 v72, 5, v8
	v_add_u32_e32 v13, 0x600, v196
	v_mad_u32_u24 v153, v149, s0, v3
	v_lshlrev_b32_e32 v3, 2, v72
	v_lshrrev_b32_e32 v74, 5, v9
	v_add_u32_e32 v62, 0x100, v196
	v_add_u32_e32 v15, 0x700, v196
	v_lshrrev_b32_e32 v64, 5, v196
	v_mad_u32_u24 v154, v149, s0, v3
	v_lshlrev_b32_e32 v3, 2, v74
	v_lshrrev_b32_e32 v76, 5, v13
	v_lshlrev_b32_e32 v23, 2, v64
	v_lshrrev_b32_e32 v66, 5, v62
	v_mad_u32_u24 v155, v149, s0, v3
	v_lshlrev_b32_e32 v3, 2, v76
	v_lshrrev_b32_e32 v78, 5, v15
	v_mad_u32_u24 v150, v149, s0, v23
	v_lshlrev_b32_e32 v23, 2, v66
	v_mad_u32_u24 v156, v149, s0, v3
	v_lshlrev_b32_e32 v3, 2, v78
	v_mad_u32_u24 v151, v149, s0, v23
	v_mad_u32_u24 v157, v149, s0, v3
	s_load_dwordx2 s[0:1], s[92:93], 0xd0
	s_load_dwordx8 s[4:11], s[92:93], 0x190
	v_lshrrev_b32_e32 v3, 1, v196
	v_lshrrev_b32_e32 v73, 6, v8
	v_and_b32_e32 v8, 0x1c0, v3
	v_and_b32_e32 v0, 63, v196
	v_mov_b32_e32 v60, 0
	v_and_b32_e32 v4, 30, v4
	v_lshlrev_b32_e32 v159, 7, v8
	v_lshlrev_b32_e32 v160, 2, v8
	v_bfrev_b32_e32 v8, 0.5
	v_lshlrev_b32_e32 v2, 2, v0
	v_lshrrev_b32_e32 v138, 6, v9
	v_lshl_or_b32 v161, v3, 2, v8
	v_mov_b32_e32 v3, v60
	v_lshlrev_b32_e32 v8, 1, v4
	v_mov_b32_e32 v9, v60
	s_load_dwordx8 s[24:31], s[92:93], 0x68
	s_load_dwordx2 s[44:45], s[92:93], 0x108
	s_load_dwordx2 s[52:53], s[92:93], 0xf8
	s_waitcnt lgkmcnt(0)
	v_lshl_add_u64 v[82:83], s[0:1], 0, v[2:3]
	v_lshl_add_u64 v[90:91], s[6:7], 0, v[8:9]
	s_load_dwordx2 s[0:1], s[92:93], 0x10
	s_load_dwordx2 s[6:7], s[92:93], 0x20
	v_mov_b32_e32 v197, v60
	v_lshrrev_b32_e32 v71, 6, v6
	v_and_b32_e32 v6, 0x7f, v196
	v_lshlrev_b64 v[100:101], 2, v[196:197]
	v_lshlrev_b32_e32 v80, 2, v6
	v_mov_b32_e32 v81, v60
	v_lshl_add_u64 v[104:105], s[26:27], 0, v[100:101]
	s_waitcnt lgkmcnt(0)
	v_lshl_add_u64 v[108:109], s[0:1], 0, v[100:101]
	s_mov_b64 s[0:1], 0xf400
	s_load_dwordx4 s[36:39], s[92:93], 0xb0
	s_load_dwordx2 s[54:55], s[92:93], 0x88
	v_lshl_add_u64 v[84:85], s[10:11], 0, v[8:9]
	v_lshl_add_u64 v[86:87], s[8:9], 0, v[8:9]
	v_lshl_add_u64 v[94:95], s[4:5], 0, v[8:9]
	v_lshl_add_u64 v[8:9], s[52:53], 0, v[80:81]
	s_mov_b64 s[4:5], 0x6d54000
	v_lshl_add_u64 v[110:111], v[104:105], 0, s[0:1]
	s_mul_i32 s0, s34, 0xf000
	v_lshl_add_u64 v[92:93], s[24:25], 0, v[2:3]
	s_load_dwordx2 s[24:25], s[92:93], 0x128
	s_load_dwordx4 s[40:43], s[92:93], 0x118
	v_lshl_add_u64 v[98:99], v[8:9], 0, s[4:5]
	s_add_i32 s70, s0, 0xffe20000
	v_lshl_add_u64 v[8:9], s[52:53], 0, v[100:101]
	s_mov_b64 s[0:1], 0x6393800
	s_load_dwordx4 s[48:51], s[92:93], 0x150
	v_lshl_add_u64 v[116:117], v[8:9], 0, s[0:1]
	s_mov_b64 s[0:1], 0x400
	v_lshl_add_u64 v[118:119], v[108:109], 0, s[0:1]
	s_mov_b64 s[0:1], 0x6393c00
	v_lshrrev_b32_e32 v65, 6, v196
	s_mul_i32 s2, s46, 0xf000
	v_lshl_add_u64 v[120:121], v[8:9], 0, s[0:1]
	s_lshl_b32 s0, s46, 5
	s_lshl_b32 s72, s34, 5
	s_sub_i32 s47, s34, 32
	v_mul_u32_u24_e32 v1, 0x104, v65
	v_lshrrev_b32_e32 v67, 6, v62
	v_lshrrev_b32_e32 v139, 6, v13
	v_lshrrev_b32_e32 v140, 6, v15
	s_movk_i32 s12, 0x80
	s_waitcnt lgkmcnt(0)
	v_lshl_add_u64 v[88:89], s[36:37], 0, v[2:3]
	s_add_i32 s36, s2, 0xfe020000
	s_add_i32 s71, s0, 0xfffffc00
	s_addk_i32 s72, 0xfc00
	s_mov_b32 s46, s100
	s_mov_b32 s34, s101
	s_mov_b32 s3, 0
	v_mul_u32_u24_e32 v5, 0x104, v67
	v_mul_u32_u24_e32 v7, 0x104, v69
	v_mul_u32_u24_e32 v10, 0x104, v71
	v_mul_u32_u24_e32 v11, 0x104, v73
	v_mul_u32_u24_e32 v12, 0x104, v138
	v_mul_u32_u24_e32 v14, 0x104, v139
	v_mul_u32_u24_e32 v16, 0x104, v140
	v_mul_u32_u24_e32 v17, 0x104, v142
	v_mul_u32_u24_e32 v18, 0x104, v143
	v_mul_u32_u24_e32 v19, 0x104, v144
	v_mul_u32_u24_e32 v20, 0x104, v146
	v_mul_u32_u24_e32 v21, 0x104, v147
	v_mul_u32_u24_e32 v22, 0x104, v148
	v_lshl_add_u64 v[96:97], s[6:7], 0, v[80:81]
	s_mov_b64 s[4:5], 0xf000
	s_add_u32 s56, s42, 0x400
	v_add_u32_e32 v81, v2, v1
	v_lshlrev_b32_e32 v124, 2, v0
	v_cmp_gt_u32_e64 s[0:1], s12, v196
	v_mov_b32_e32 v0, 0xfffffe00
	v_mov_b32_e32 v1, 0x800
	v_or_b32_e32 v141, 32, v65
	v_or_b32_e32 v145, 48, v65
	v_mov_b32_e32 v75, v60
	v_mov_b32_e32 v77, v60
	v_mov_b32_e32 v79, v60
	v_lshlrev_b32_e32 v158, 2, v196
	v_mov_b32_e32 v63, v60
	v_lshl_add_u64 v[102:103], s[28:29], 0, v[100:101]
	v_lshl_add_u64 v[106:107], v[104:105], 0, s[4:5]
	v_lshl_add_u64 v[112:113], v[196:197], 1, s[48:49]
	v_lshl_add_u64 v[114:115], s[42:43], 0, v[100:101]
	s_addc_u32 s57, s43, 0
	s_movk_i32 s73, 0x3a0
	s_movk_i32 s74, 0xe8
	s_movk_i32 s75, 0x1c8
	v_add_u32_e32 v162, v2, v5
	v_add_u32_e32 v163, v2, v7
	v_add_u32_e32 v164, v2, v10
	v_add_u32_e32 v165, v2, v11
	v_add_u32_e32 v166, v2, v12
	v_add_u32_e32 v167, v2, v14
	v_add_u32_e32 v168, v2, v16
	v_add_u32_e32 v169, v2, v17
	v_add_u32_e32 v170, v2, v18
	v_add_u32_e32 v171, v2, v19
	v_add_u32_e32 v172, v2, v20
	v_add_u32_e32 v173, v2, v21
	v_add_u32_e32 v174, v2, v22
	v_lshlrev_b32_e32 v122, 1, v4
	s_movk_i32 s76, 0x4000
	s_movk_i32 s77, 0x1000
	s_movk_i32 s78, 0x2000
	s_movk_i32 s79, 0x3000
	s_movk_i32 s80, 0x5000
	s_movk_i32 s81, 0x6000
	s_movk_i32 s82, 0x7000
	s_movk_i32 s83, 0x1c00
	s_mov_b32 s84, 0x6393000
	v_mov_b32_e32 v175, 0x358637bd
	s_mov_b32 s85, 0x800000
	s_mov_b32 s86, 0x4080000
	s_mov_b64 s[58:59], 0x7000
	s_mov_b64 s[60:61], 0x2000
	v_cndmask_b32_e64 v127, -1, 0, s[0:1]
	v_cndmask_b32_e64 v126, v0, v1, s[0:1]
	v_lshlrev_b32_e32 v128, 2, v6
	v_mov_b32_e32 v176, 0x1c00
	v_mov_b32_e32 v177, 0x3b000000
	s_mov_b64 s[62:63], s[2:3]
	s_branch .LBB0_614
